# fix phase indexer-key loop: the 16-lane LayerNorm sums and the rope partner fetch use DPP (quad_perm / row mirrors) instead of ds_bpermute round trips through LDS
# baseline (speedup 1.0000x reference)
; __device__ __forceinline__ void phase_fix(KP kp, int l, unsigned char* shm) {
;     ...
;   {
;     const int li = tid & 15;
;     const f32x4 gg = *(const f32x4*)(kp->idx_g + l * 64 + li * 4), bb = *(const f32x4*)(kp->idx_b + l * 64 + li * 4);
;     for (int rb = bid * 32; rb < MT; rb += nb * 32) {
;       const int r = rb + (tid >> 4);
;       const bool samp = r >= MP;
;       const int sr = r - MP;
;       const int pos = samp ? 2048 + (sr & 31) : (r & 4095);
;       const f32x4 x = *(const f32x4*)((const float*)(ws + W_KIRAW) + (size_t)r * 64 + li * 4);
;       float s = x[0] + x[1] + x[2] + x[3];
;       s += __shfl_xor(s, 1); s += __shfl_xor(s, 2); s += __shfl_xor(s, 4); s += __shfl_xor(s, 8);
;       const float mean = s * (1.f / 64.f);
;       const f32x4 d = x - mean;
;       float ss = d[0] * d[0] + d[1] * d[1] + d[2] * d[2] + d[3] * d[3];
;       ss += __shfl_xor(ss, 1); ss += __shfl_xor(ss, 2); ss += __shfl_xor(ss, 4); ss += __shfl_xor(ss, 8);
;       const float rstd = rsqrtf(ss * (1.f / 64.f) + LN_EPS);
;       f32x4 y = d * rstd * gg + bb;
;       f32x4 pr;
; #pragma unroll
;       for (int e = 0; e < 4; ++e) pr[e] = __shfl_xor(y[e], 2);
;       if (li < 4) {
;         const int i0 = (li & 1) * 4;
;         const f32x4 t0 = *(const f32x4*)(rope + (size_t)pos * 16 + i0 * 2), t1 = *(const f32x4*)(rope + (size_t)pos * 16 + i0 * 2 + 4);
;         const float cc[4] = {t0[0], t0[2], t1[0], t1[2]}, sn[4] = {t0[1], t0[3], t1[1], t1[3]};
; #pragma unroll
;         for (int e = 0; e < 4; ++e) y[e] = (li < 2) ? (y[e] * cc[e] - pr[e] * sn[e]) : (pr[e] * sn[e] + y[e] * cc[e]);
;       }
.LBB0_2798:
	s_or_b64 exec, exec, s[0:1]
	v_readlane_b32 s0, v255, 14
	v_readlane_b32 s12, v254, 2
	v_readlane_b32 s1, v255, 15
	v_readlane_b32 s13, v254, 3
	v_mov_b32_e32 v27, v244
	s_xor_b64 s[0:1], s[0:1], -1
	s_waitcnt lgkmcnt(0)
	s_barrier
	s_load_dwordx2 s[14:15], s[12:13], 0xb0
	v_writelane_b32 v255, s0, 25
	v_and_b32_e32 v26, 15, v27
	s_nop 0
	v_writelane_b32 v255, s1, 26
	v_readlane_b32 s0, v254, 10
	v_readlane_b32 s1, v254, 11
	s_andn2_b64 vcc, exec, s[0:1]
	s_cbranch_vccnz .LBB0_2807
	s_load_dwordx4 s[0:3], s[12:13], 0x30
	v_readlane_b32 s4, v255, 20
	v_readlane_b32 s5, v255, 21
	v_readlane_b32 s22, v255, 22
	s_mov_b32 s11, s5
	s_lshl_b32 s10, s22, 6
	s_lshl_b64 s[4:5], s[10:11], 2
	s_waitcnt lgkmcnt(0)
	s_add_u32 s2, s2, s4
	s_addc_u32 s3, s3, s5
	v_lshlrev_b32_e32 v9, 4, v26
	s_add_u32 s0, s0, s4
	s_addc_u32 s1, s1, s5
	global_load_dwordx4 v[0:3], v9, s[2:3]
	global_load_dwordx4 v[4:7], v9, s[0:1]
	v_and_b32_e32 v11, 64, v252
	v_xor_b32_e32 v10, 1, v252
	v_add_u32_e32 v11, 64, v11
	v_cmp_lt_i32_e32 vcc, v10, v11
	v_ashrrev_i32_e32 v28, 4, v27
	v_and_b32_e32 v14, 31, v28
	v_cndmask_b32_e32 v10, v252, v10, vcc
	v_lshlrev_b32_e32 v30, 2, v10
	v_xor_b32_e32 v10, 2, v252
	v_cmp_lt_i32_e32 vcc, v10, v11
	s_mov_b64 s[0:1], 0x3980000
	s_movk_i32 s4, 0xe0
	v_cndmask_b32_e32 v10, v252, v10, vcc
	v_lshlrev_b32_e32 v31, 2, v10
	v_xor_b32_e32 v10, 4, v252
	v_cmp_lt_i32_e32 vcc, v10, v11
	s_mov_b32 s5, s11
	v_readlane_b32 s23, v255, 23
	v_cndmask_b32_e32 v10, v252, v10, vcc
	v_lshlrev_b32_e32 v32, 2, v10
	v_xor_b32_e32 v10, 8, v252
	v_cmp_lt_i32_e32 vcc, v10, v11
	s_add_u32 s6, s14, 0xbf80000
	v_lshlrev_b32_e32 v8, 2, v26
	v_cndmask_b32_e32 v10, v252, v10, vcc
	v_lshlrev_b32_e32 v33, 2, v10
	v_lshlrev_b32_e32 v10, 5, v27
	v_and_b32_e32 v16, 32, v10
	v_lshl_add_u64 v[10:11], s[14:15], 0, v[16:17]
	v_lshl_add_u64 v[12:13], v[10:11], 0, s[0:1]
	v_and_or_b32 v10, v9, 32, v14
	v_and_or_b32 v9, v9, s4, v14
	v_writelane_b32 v255, s4, 20
	s_addc_u32 s7, s15, 0
	s_add_u32 s8, s14, 0xbb80000
	v_writelane_b32 v255, s5, 21
	s_mov_b32 s4, s22
	v_and_b32_e32 v11, 4, v8
	s_mov_b32 s23, s11
	v_writelane_b32 v255, s4, 22
	v_or_b32_e32 v29, 0x800, v14
	s_addc_u32 s9, s15, 0
	v_lshlrev_b32_e32 v14, 1, v11
	v_writelane_b32 v255, s5, 23
	s_lshl_b64 s[4:5], s[22:23], 23
	v_readlane_b32 s23, v254, 12
	v_lshl_or_b32 v16, v9, 4, v14
	v_lshl_or_b32 v9, v10, 3, v11
	v_add_u32_e32 v10, s23, v28
	s_lshl_b32 s20, s22, 9
	v_ashrrev_i32_e32 v11, 31, v10
	s_add_u32 s21, s4, 0xc200000
	v_lshlrev_b64 v[18:19], 8, v[10:11]
	v_cmp_gt_u32_e64 s[0:1], 2, v26
	v_cmp_gt_u32_e64 s[2:3], 4, v26
	v_lshrrev_b32_e32 v34, 2, v26
	v_lshl_add_u64 v[14:15], s[14:15], 0, v[16:17]
	s_addc_u32 s22, s5, 0
	v_lshl_or_b32 v18, v26, 4, v18
	v_lshlrev_b32_e32 v35, 1, v9
	v_lshlrev_b32_e32 v20, 2, v8
	v_readlane_b32 s24, v255, 4
	v_readlane_b32 s25, v255, 5
	v_lshl_add_u64 v[220:221], s[6:7], 0, v[18:19]
	global_load_dwordx4 v[200:203], v[220:221], off
	v_lshl_add_u64 v[220:221], v[220:221], 0, s[24:25]
	global_load_dwordx4 v[204:207], v[220:221], off
	v_lshl_add_u64 v[220:221], v[220:221], 0, s[24:25]
	global_load_dwordx4 v[208:211], v[220:221], off
	v_lshl_add_u64 v[220:221], v[220:221], 0, s[24:25]
	global_load_dwordx4 v[212:215], v[220:221], off
	v_lshl_add_u64 v[220:221], v[220:221], 0, s[24:25]
	global_load_dwordx4 v[216:219], v[220:221], off
	s_mov_b32 s4, 0x800000
	s_mov_b32 s10, 0x8000
	s_waitcnt vmcnt(0)
	v_mov_b32_e32 v8, v200
	v_mov_b32_e32 v9, v201
	v_mov_b32_e32 v10, v202
	v_mov_b32_e32 v11, v203
	v_add_f32_e32 v16, v8, v9
	v_add_f32_e32 v16, v10, v16
	v_add_f32_e32 v16, v11, v16
	s_nop 1
	v_add_f32_dpp v16, v16, v16 quad_perm:[1,0,3,2] row_mask:0xf bank_mask:0xf
	s_nop 1
	v_add_f32_dpp v16, v16, v16 quad_perm:[2,3,0,1] row_mask:0xf bank_mask:0xf
	s_nop 1
	v_add_f32_dpp v16, v16, v16 row_half_mirror row_mask:0xf bank_mask:0xf
	s_nop 1
	v_add_f32_dpp v16, v16, v16 row_mirror row_mask:0xf bank_mask:0xf
	v_fmamk_f32 v9, v16, 0xbc800000, v9
	v_fmamk_f32 v8, v16, 0xbc800000, v8
	v_fmamk_f32 v11, v16, 0xbc800000, v11
	v_fmac_f32_e32 v10, 0xbc800000, v16
	v_pk_mul_f32 v[24:25], v[8:9], v[8:9]
	v_pk_mul_f32 v[22:23], v[10:11], v[10:11]
	v_add_f32_e32 v16, v24, v25
	v_add_f32_e32 v16, v22, v16
	v_add_f32_e32 v16, v23, v16
	s_nop 1
	v_add_f32_dpp v16, v16, v16 quad_perm:[1,0,3,2] row_mask:0xf bank_mask:0xf
	s_nop 1
	v_add_f32_dpp v16, v16, v16 quad_perm:[2,3,0,1] row_mask:0xf bank_mask:0xf
	s_nop 1
	v_add_f32_dpp v16, v16, v16 row_half_mirror row_mask:0xf bank_mask:0xf
	s_nop 1
	v_add_f32_dpp v16, v16, v16 row_mirror row_mask:0xf bank_mask:0xf
	v_fmamk_f32 v16, v16, 0x3c800000, v249
	v_mul_f32_e32 v21, 0x4b800000, v16
	v_cmp_gt_f32_e32 vcc, s4, v16
	s_movk_i32 s4, 0x7fff
	s_nop 0
	v_cndmask_b32_e32 v16, v16, v21, vcc
	v_rsq_f32_e32 v16, v16
	s_nop 0
	v_mul_f32_e32 v21, 0x45800000, v16
	v_cndmask_b32_e32 v16, v16, v21, vcc
	v_pk_mul_f32 v[8:9], v[8:9], v[16:17] op_sel_hi:[1,0]
	v_pk_mul_f32 v[10:11], v[10:11], v[16:17] op_sel_hi:[1,0]
	v_pk_fma_f32 v[8:9], v[4:5], v[8:9], v[0:1]
	v_pk_fma_f32 v[10:11], v[6:7], v[10:11], v[2:3]
	s_nop 1
	v_mov_b32_dpp v22, v8 quad_perm:[2,3,0,1] row_mask:0xf bank_mask:0xf
	v_mov_b32_dpp v23, v9 quad_perm:[2,3,0,1] row_mask:0xf bank_mask:0xf
	v_mov_b32_dpp v24, v10 quad_perm:[2,3,0,1] row_mask:0xf bank_mask:0xf
	v_mov_b32_dpp v25, v11 quad_perm:[2,3,0,1] row_mask:0xf bank_mask:0xf
	v_add_u32_e32 v21, s23, v28
	v_cmp_lt_i32_e64 s[4:5], s4, v21
	v_cmp_gt_i32_e32 vcc, s10, v21
	s_and_saveexec_b64 s[10:11], s[2:3]
	s_cbranch_execz .Lfixki0_a
	v_and_b32_e32 v16, 0xfff, v21
	v_cndmask_b32_e64 v16, v16, v29, s[4:5]
	v_lshlrev_b32_e32 v16, 6, v16
	v_lshl_add_u64 v[40:41], v[12:13], 0, v[16:17]
	global_load_dwordx4 v[36:39], v[40:41], off
	s_nop 0
	global_load_dwordx4 v[40:43], v[40:41], off offset:16
	s_waitcnt vmcnt(1)
	v_mov_b32_e32 v45, v38
	v_mov_b32_e32 v38, v37
	s_waitcnt vmcnt(0)
	v_mov_b32_e32 v37, v42
	v_mov_b32_e32 v42, v41
	s_waitcnt lgkmcnt(2)
	v_pk_mul_f32 v[22:23], v[38:39], v[22:23]
	s_waitcnt lgkmcnt(0)
	v_pk_mul_f32 v[24:25], v[42:43], v[24:25]
	v_mov_b32_e32 v44, v36
	v_mov_b32_e32 v36, v40
	v_cndmask_b32_e64 v23, v23, -v23, s[0:1]
	v_cndmask_b32_e64 v22, v22, -v22, s[0:1]
	v_cndmask_b32_e64 v25, v25, -v25, s[0:1]
	v_cndmask_b32_e64 v24, v24, -v24, s[0:1]
	v_pk_fma_f32 v[8:9], v[8:9], v[44:45], v[22:23]
	v_pk_fma_f32 v[10:11], v[10:11], v[36:37], v[24:25]

; __device__ __forceinline__ void phase_fix(KP kp, int l, unsigned char* shm) {
;     ...
;     for (int rb = bid * 32; rb < MT; rb += nb * 32) {
;       const int r = rb + (tid >> 4);
;       const bool samp = r >= MP;
;       const int sr = r - MP;
;       const int pos = samp ? 2048 + (sr & 31) : (r & 4095);
;       const f32x4 x = *(const f32x4*)((const float*)(ws + W_KIRAW) + (size_t)r * 64 + li * 4);
;       float s = x[0] + x[1] + x[2] + x[3];
;       s += __shfl_xor(s, 1); s += __shfl_xor(s, 2); s += __shfl_xor(s, 4); s += __shfl_xor(s, 8);
;       const float mean = s * (1.f / 64.f);
;       const f32x4 d = x - mean;
;       float ss = d[0] * d[0] + d[1] * d[1] + d[2] * d[2] + d[3] * d[3];
;       ss += __shfl_xor(ss, 1); ss += __shfl_xor(ss, 2); ss += __shfl_xor(ss, 4); ss += __shfl_xor(ss, 8);
;       const float rstd = rsqrtf(ss * (1.f / 64.f) + LN_EPS);
;       f32x4 y = d * rstd * gg + bb;
;       f32x4 pr;
; #pragma unroll
;       for (int e = 0; e < 4; ++e) pr[e] = __shfl_xor(y[e], 2);
;       if (li < 4) {
;         const int i0 = (li & 1) * 4;
;         const f32x4 t0 = *(const f32x4*)(rope + (size_t)pos * 16 + i0 * 2), t1 = *(const f32x4*)(rope + (size_t)pos * 16 + i0 * 2 + 4);
;         const float cc[4] = {t0[0], t0[2], t1[0], t1[2]}, sn[4] = {t0[1], t0[3], t1[1], t1[3]};
; #pragma unroll
;         for (int e = 0; e < 4; ++e) y[e] = (li < 2) ? (y[e] * cc[e] - pr[e] * sn[e]) : (pr[e] * sn[e] + y[e] * cc[e]);
;       }
.Lfixki0_t:
	s_or_b64 exec, exec, s[10:11]
	s_waitcnt lgkmcnt(0)
	v_readlane_b32 s4, v255, 2
	v_readlane_b32 s5, v255, 3
	s_add_i32 s23, s23, s4
	v_readlane_b32 s4, v255, 4
	v_readlane_b32 s5, v255, 5
	s_cmp_gt_i32 s23, 0x81ff
	s_nop 0
	v_lshl_add_u64 v[18:19], v[18:19], 0, s[4:5]
	s_cbranch_scc1 .LBB0_2807
	s_mov_b32 s4, 0x800000
	s_mov_b32 s10, 0x8000
	v_mov_b32_e32 v8, v204
	v_mov_b32_e32 v9, v205
	v_mov_b32_e32 v10, v206
	v_mov_b32_e32 v11, v207
	v_add_f32_e32 v16, v8, v9
	v_add_f32_e32 v16, v10, v16
	v_add_f32_e32 v16, v11, v16
	s_nop 1
	v_add_f32_dpp v16, v16, v16 quad_perm:[1,0,3,2] row_mask:0xf bank_mask:0xf
	s_nop 1
	v_add_f32_dpp v16, v16, v16 quad_perm:[2,3,0,1] row_mask:0xf bank_mask:0xf
	s_nop 1
	v_add_f32_dpp v16, v16, v16 row_half_mirror row_mask:0xf bank_mask:0xf
	s_nop 1
	v_add_f32_dpp v16, v16, v16 row_mirror row_mask:0xf bank_mask:0xf
	v_fmamk_f32 v9, v16, 0xbc800000, v9
	v_fmamk_f32 v8, v16, 0xbc800000, v8
	v_fmamk_f32 v11, v16, 0xbc800000, v11
	v_fmac_f32_e32 v10, 0xbc800000, v16
	v_pk_mul_f32 v[24:25], v[8:9], v[8:9]
	v_pk_mul_f32 v[22:23], v[10:11], v[10:11]
	v_add_f32_e32 v16, v24, v25
	v_add_f32_e32 v16, v22, v16
	v_add_f32_e32 v16, v23, v16
	s_nop 1
	v_add_f32_dpp v16, v16, v16 quad_perm:[1,0,3,2] row_mask:0xf bank_mask:0xf
	s_nop 1
	v_add_f32_dpp v16, v16, v16 quad_perm:[2,3,0,1] row_mask:0xf bank_mask:0xf
	s_nop 1
	v_add_f32_dpp v16, v16, v16 row_half_mirror row_mask:0xf bank_mask:0xf
	s_nop 1
	v_add_f32_dpp v16, v16, v16 row_mirror row_mask:0xf bank_mask:0xf
	v_fmamk_f32 v16, v16, 0x3c800000, v249
	v_mul_f32_e32 v21, 0x4b800000, v16
	v_cmp_gt_f32_e32 vcc, s4, v16
	s_movk_i32 s4, 0x7fff
	s_nop 0
	v_cndmask_b32_e32 v16, v16, v21, vcc
	v_rsq_f32_e32 v16, v16
	s_nop 0
	v_mul_f32_e32 v21, 0x45800000, v16
	v_cndmask_b32_e32 v16, v16, v21, vcc
	v_pk_mul_f32 v[8:9], v[8:9], v[16:17] op_sel_hi:[1,0]
	v_pk_mul_f32 v[10:11], v[10:11], v[16:17] op_sel_hi:[1,0]
	v_pk_fma_f32 v[8:9], v[4:5], v[8:9], v[0:1]
	v_pk_fma_f32 v[10:11], v[6:7], v[10:11], v[2:3]
	s_nop 1
	v_mov_b32_dpp v22, v8 quad_perm:[2,3,0,1] row_mask:0xf bank_mask:0xf
	v_mov_b32_dpp v23, v9 quad_perm:[2,3,0,1] row_mask:0xf bank_mask:0xf
	v_mov_b32_dpp v24, v10 quad_perm:[2,3,0,1] row_mask:0xf bank_mask:0xf
	v_mov_b32_dpp v25, v11 quad_perm:[2,3,0,1] row_mask:0xf bank_mask:0xf
	v_add_u32_e32 v21, s23, v28
	v_cmp_lt_i32_e64 s[4:5], s4, v21
	v_cmp_gt_i32_e32 vcc, s10, v21
	s_and_saveexec_b64 s[10:11], s[2:3]
	s_cbranch_execz .Lfixki1_a
	v_and_b32_e32 v16, 0xfff, v21
	v_cndmask_b32_e64 v16, v16, v29, s[4:5]
	v_lshlrev_b32_e32 v16, 6, v16
	v_lshl_add_u64 v[40:41], v[12:13], 0, v[16:17]
	global_load_dwordx4 v[36:39], v[40:41], off
	s_nop 0
	global_load_dwordx4 v[40:43], v[40:41], off offset:16
	s_waitcnt vmcnt(1)
	v_mov_b32_e32 v45, v38
	v_mov_b32_e32 v38, v37
	s_waitcnt vmcnt(0)
	v_mov_b32_e32 v37, v42
	v_mov_b32_e32 v42, v41
	s_waitcnt lgkmcnt(2)
	v_pk_mul_f32 v[22:23], v[38:39], v[22:23]
	s_waitcnt lgkmcnt(0)
	v_pk_mul_f32 v[24:25], v[42:43], v[24:25]
	v_mov_b32_e32 v44, v36
	v_mov_b32_e32 v36, v40
	v_cndmask_b32_e64 v23, v23, -v23, s[0:1]
	v_cndmask_b32_e64 v22, v22, -v22, s[0:1]
	v_cndmask_b32_e64 v25, v25, -v25, s[0:1]
	v_cndmask_b32_e64 v24, v24, -v24, s[0:1]
	v_pk_fma_f32 v[8:9], v[8:9], v[44:45], v[22:23]
	v_pk_fma_f32 v[10:11], v[10:11], v[36:37], v[24:25]

; __device__ __forceinline__ void phase_fix(KP kp, int l, unsigned char* shm) {
;     ...
;     for (int rb = bid * 32; rb < MT; rb += nb * 32) {
;       const int r = rb + (tid >> 4);
;       const bool samp = r >= MP;
;       const int sr = r - MP;
;       const int pos = samp ? 2048 + (sr & 31) : (r & 4095);
;       const f32x4 x = *(const f32x4*)((const float*)(ws + W_KIRAW) + (size_t)r * 64 + li * 4);
;       float s = x[0] + x[1] + x[2] + x[3];
;       s += __shfl_xor(s, 1); s += __shfl_xor(s, 2); s += __shfl_xor(s, 4); s += __shfl_xor(s, 8);
;       const float mean = s * (1.f / 64.f);
;       const f32x4 d = x - mean;
;       float ss = d[0] * d[0] + d[1] * d[1] + d[2] * d[2] + d[3] * d[3];
;       ss += __shfl_xor(ss, 1); ss += __shfl_xor(ss, 2); ss += __shfl_xor(ss, 4); ss += __shfl_xor(ss, 8);
;       const float rstd = rsqrtf(ss * (1.f / 64.f) + LN_EPS);
;       f32x4 y = d * rstd * gg + bb;
;       f32x4 pr;
; #pragma unroll
;       for (int e = 0; e < 4; ++e) pr[e] = __shfl_xor(y[e], 2);
;       if (li < 4) {
;         const int i0 = (li & 1) * 4;
;         const f32x4 t0 = *(const f32x4*)(rope + (size_t)pos * 16 + i0 * 2), t1 = *(const f32x4*)(rope + (size_t)pos * 16 + i0 * 2 + 4);
;         const float cc[4] = {t0[0], t0[2], t1[0], t1[2]}, sn[4] = {t0[1], t0[3], t1[1], t1[3]};
; #pragma unroll
;         for (int e = 0; e < 4; ++e) y[e] = (li < 2) ? (y[e] * cc[e] - pr[e] * sn[e]) : (pr[e] * sn[e] + y[e] * cc[e]);
;       }
.Lfixki1_t:
	s_or_b64 exec, exec, s[10:11]
	s_waitcnt lgkmcnt(0)
	v_readlane_b32 s4, v255, 2
	v_readlane_b32 s5, v255, 3
	s_add_i32 s23, s23, s4
	v_readlane_b32 s4, v255, 4
	v_readlane_b32 s5, v255, 5
	s_cmp_gt_i32 s23, 0x81ff
	s_nop 0
	v_lshl_add_u64 v[18:19], v[18:19], 0, s[4:5]
	s_cbranch_scc1 .LBB0_2807
	s_mov_b32 s4, 0x800000
	s_mov_b32 s10, 0x8000
	v_mov_b32_e32 v8, v208
	v_mov_b32_e32 v9, v209
	v_mov_b32_e32 v10, v210
	v_mov_b32_e32 v11, v211
	v_add_f32_e32 v16, v8, v9
	v_add_f32_e32 v16, v10, v16
	v_add_f32_e32 v16, v11, v16
	s_nop 1
	v_add_f32_dpp v16, v16, v16 quad_perm:[1,0,3,2] row_mask:0xf bank_mask:0xf
	s_nop 1
	v_add_f32_dpp v16, v16, v16 quad_perm:[2,3,0,1] row_mask:0xf bank_mask:0xf
	s_nop 1
	v_add_f32_dpp v16, v16, v16 row_half_mirror row_mask:0xf bank_mask:0xf
	s_nop 1
	v_add_f32_dpp v16, v16, v16 row_mirror row_mask:0xf bank_mask:0xf
	v_fmamk_f32 v9, v16, 0xbc800000, v9
	v_fmamk_f32 v8, v16, 0xbc800000, v8
	v_fmamk_f32 v11, v16, 0xbc800000, v11
	v_fmac_f32_e32 v10, 0xbc800000, v16
	v_pk_mul_f32 v[24:25], v[8:9], v[8:9]
	v_pk_mul_f32 v[22:23], v[10:11], v[10:11]
	v_add_f32_e32 v16, v24, v25
	v_add_f32_e32 v16, v22, v16
	v_add_f32_e32 v16, v23, v16
	s_nop 1
	v_add_f32_dpp v16, v16, v16 quad_perm:[1,0,3,2] row_mask:0xf bank_mask:0xf
	s_nop 1
	v_add_f32_dpp v16, v16, v16 quad_perm:[2,3,0,1] row_mask:0xf bank_mask:0xf
	s_nop 1
	v_add_f32_dpp v16, v16, v16 row_half_mirror row_mask:0xf bank_mask:0xf
	s_nop 1
	v_add_f32_dpp v16, v16, v16 row_mirror row_mask:0xf bank_mask:0xf
	v_fmamk_f32 v16, v16, 0x3c800000, v249
	v_mul_f32_e32 v21, 0x4b800000, v16
	v_cmp_gt_f32_e32 vcc, s4, v16
	s_movk_i32 s4, 0x7fff
	s_nop 0
	v_cndmask_b32_e32 v16, v16, v21, vcc
	v_rsq_f32_e32 v16, v16
	s_nop 0
	v_mul_f32_e32 v21, 0x45800000, v16
	v_cndmask_b32_e32 v16, v16, v21, vcc
	v_pk_mul_f32 v[8:9], v[8:9], v[16:17] op_sel_hi:[1,0]
	v_pk_mul_f32 v[10:11], v[10:11], v[16:17] op_sel_hi:[1,0]
	v_pk_fma_f32 v[8:9], v[4:5], v[8:9], v[0:1]
	v_pk_fma_f32 v[10:11], v[6:7], v[10:11], v[2:3]
	s_nop 1
	v_mov_b32_dpp v22, v8 quad_perm:[2,3,0,1] row_mask:0xf bank_mask:0xf
	v_mov_b32_dpp v23, v9 quad_perm:[2,3,0,1] row_mask:0xf bank_mask:0xf
	v_mov_b32_dpp v24, v10 quad_perm:[2,3,0,1] row_mask:0xf bank_mask:0xf
	v_mov_b32_dpp v25, v11 quad_perm:[2,3,0,1] row_mask:0xf bank_mask:0xf
	v_add_u32_e32 v21, s23, v28
	v_cmp_lt_i32_e64 s[4:5], s4, v21
	v_cmp_gt_i32_e32 vcc, s10, v21
	s_and_saveexec_b64 s[10:11], s[2:3]
	s_cbranch_execz .Lfixki2_a
	v_and_b32_e32 v16, 0xfff, v21
	v_cndmask_b32_e64 v16, v16, v29, s[4:5]
	v_lshlrev_b32_e32 v16, 6, v16
	v_lshl_add_u64 v[40:41], v[12:13], 0, v[16:17]
	global_load_dwordx4 v[36:39], v[40:41], off
	s_nop 0
	global_load_dwordx4 v[40:43], v[40:41], off offset:16
	s_waitcnt vmcnt(1)
	v_mov_b32_e32 v45, v38
	v_mov_b32_e32 v38, v37
	s_waitcnt vmcnt(0)
	v_mov_b32_e32 v37, v42
	v_mov_b32_e32 v42, v41
	s_waitcnt lgkmcnt(2)
	v_pk_mul_f32 v[22:23], v[38:39], v[22:23]
	s_waitcnt lgkmcnt(0)
	v_pk_mul_f32 v[24:25], v[42:43], v[24:25]
	v_mov_b32_e32 v44, v36
	v_mov_b32_e32 v36, v40
	v_cndmask_b32_e64 v23, v23, -v23, s[0:1]
	v_cndmask_b32_e64 v22, v22, -v22, s[0:1]
	v_cndmask_b32_e64 v25, v25, -v25, s[0:1]
	v_cndmask_b32_e64 v24, v24, -v24, s[0:1]
	v_pk_fma_f32 v[8:9], v[8:9], v[44:45], v[22:23]
	v_pk_fma_f32 v[10:11], v[10:11], v[36:37], v[24:25]

; __device__ __forceinline__ void phase_fix(KP kp, int l, unsigned char* shm) {
;     ...
;     for (int rb = bid * 32; rb < MT; rb += nb * 32) {
;       const int r = rb + (tid >> 4);
;       const bool samp = r >= MP;
;       const int sr = r - MP;
;       const int pos = samp ? 2048 + (sr & 31) : (r & 4095);
;       const f32x4 x = *(const f32x4*)((const float*)(ws + W_KIRAW) + (size_t)r * 64 + li * 4);
;       float s = x[0] + x[1] + x[2] + x[3];
;       s += __shfl_xor(s, 1); s += __shfl_xor(s, 2); s += __shfl_xor(s, 4); s += __shfl_xor(s, 8);
;       const float mean = s * (1.f / 64.f);
;       const f32x4 d = x - mean;
;       float ss = d[0] * d[0] + d[1] * d[1] + d[2] * d[2] + d[3] * d[3];
;       ss += __shfl_xor(ss, 1); ss += __shfl_xor(ss, 2); ss += __shfl_xor(ss, 4); ss += __shfl_xor(ss, 8);
;       const float rstd = rsqrtf(ss * (1.f / 64.f) + LN_EPS);
;       f32x4 y = d * rstd * gg + bb;
;       f32x4 pr;
; #pragma unroll
;       for (int e = 0; e < 4; ++e) pr[e] = __shfl_xor(y[e], 2);
;       if (li < 4) {
;         const int i0 = (li & 1) * 4;
;         const f32x4 t0 = *(const f32x4*)(rope + (size_t)pos * 16 + i0 * 2), t1 = *(const f32x4*)(rope + (size_t)pos * 16 + i0 * 2 + 4);
;         const float cc[4] = {t0[0], t0[2], t1[0], t1[2]}, sn[4] = {t0[1], t0[3], t1[1], t1[3]};
; #pragma unroll
;         for (int e = 0; e < 4; ++e) y[e] = (li < 2) ? (y[e] * cc[e] - pr[e] * sn[e]) : (pr[e] * sn[e] + y[e] * cc[e]);
;       }
.Lfixki2_t:
	s_or_b64 exec, exec, s[10:11]
	s_waitcnt lgkmcnt(0)
	v_readlane_b32 s4, v255, 2
	v_readlane_b32 s5, v255, 3
	s_add_i32 s23, s23, s4
	v_readlane_b32 s4, v255, 4
	v_readlane_b32 s5, v255, 5
	s_cmp_gt_i32 s23, 0x81ff
	s_nop 0
	v_lshl_add_u64 v[18:19], v[18:19], 0, s[4:5]
	s_cbranch_scc1 .LBB0_2807
	s_mov_b32 s4, 0x800000
	s_mov_b32 s10, 0x8000
	v_mov_b32_e32 v8, v212
	v_mov_b32_e32 v9, v213
	v_mov_b32_e32 v10, v214
	v_mov_b32_e32 v11, v215
	v_add_f32_e32 v16, v8, v9
	v_add_f32_e32 v16, v10, v16
	v_add_f32_e32 v16, v11, v16
	s_nop 1
	v_add_f32_dpp v16, v16, v16 quad_perm:[1,0,3,2] row_mask:0xf bank_mask:0xf
	s_nop 1
	v_add_f32_dpp v16, v16, v16 quad_perm:[2,3,0,1] row_mask:0xf bank_mask:0xf
	s_nop 1
	v_add_f32_dpp v16, v16, v16 row_half_mirror row_mask:0xf bank_mask:0xf
	s_nop 1
	v_add_f32_dpp v16, v16, v16 row_mirror row_mask:0xf bank_mask:0xf
	v_fmamk_f32 v9, v16, 0xbc800000, v9
	v_fmamk_f32 v8, v16, 0xbc800000, v8
	v_fmamk_f32 v11, v16, 0xbc800000, v11
	v_fmac_f32_e32 v10, 0xbc800000, v16
	v_pk_mul_f32 v[24:25], v[8:9], v[8:9]
	v_pk_mul_f32 v[22:23], v[10:11], v[10:11]
	v_add_f32_e32 v16, v24, v25
	v_add_f32_e32 v16, v22, v16
	v_add_f32_e32 v16, v23, v16
	s_nop 1
	v_add_f32_dpp v16, v16, v16 quad_perm:[1,0,3,2] row_mask:0xf bank_mask:0xf
	s_nop 1
	v_add_f32_dpp v16, v16, v16 quad_perm:[2,3,0,1] row_mask:0xf bank_mask:0xf
	s_nop 1
	v_add_f32_dpp v16, v16, v16 row_half_mirror row_mask:0xf bank_mask:0xf
	s_nop 1
	v_add_f32_dpp v16, v16, v16 row_mirror row_mask:0xf bank_mask:0xf
	v_fmamk_f32 v16, v16, 0x3c800000, v249
	v_mul_f32_e32 v21, 0x4b800000, v16
	v_cmp_gt_f32_e32 vcc, s4, v16
	s_movk_i32 s4, 0x7fff
	s_nop 0
	v_cndmask_b32_e32 v16, v16, v21, vcc
	v_rsq_f32_e32 v16, v16
	s_nop 0
	v_mul_f32_e32 v21, 0x45800000, v16
	v_cndmask_b32_e32 v16, v16, v21, vcc
	v_pk_mul_f32 v[8:9], v[8:9], v[16:17] op_sel_hi:[1,0]
	v_pk_mul_f32 v[10:11], v[10:11], v[16:17] op_sel_hi:[1,0]
	v_pk_fma_f32 v[8:9], v[4:5], v[8:9], v[0:1]
	v_pk_fma_f32 v[10:11], v[6:7], v[10:11], v[2:3]
	s_nop 1
	v_mov_b32_dpp v22, v8 quad_perm:[2,3,0,1] row_mask:0xf bank_mask:0xf
	v_mov_b32_dpp v23, v9 quad_perm:[2,3,0,1] row_mask:0xf bank_mask:0xf
	v_mov_b32_dpp v24, v10 quad_perm:[2,3,0,1] row_mask:0xf bank_mask:0xf
	v_mov_b32_dpp v25, v11 quad_perm:[2,3,0,1] row_mask:0xf bank_mask:0xf
	v_add_u32_e32 v21, s23, v28
	v_cmp_lt_i32_e64 s[4:5], s4, v21
	v_cmp_gt_i32_e32 vcc, s10, v21
	s_and_saveexec_b64 s[10:11], s[2:3]
	s_cbranch_execz .Lfixki3_a
	v_and_b32_e32 v16, 0xfff, v21
	v_cndmask_b32_e64 v16, v16, v29, s[4:5]
	v_lshlrev_b32_e32 v16, 6, v16
	v_lshl_add_u64 v[40:41], v[12:13], 0, v[16:17]
	global_load_dwordx4 v[36:39], v[40:41], off
	s_nop 0
	global_load_dwordx4 v[40:43], v[40:41], off offset:16
	s_waitcnt vmcnt(1)
	v_mov_b32_e32 v45, v38
	v_mov_b32_e32 v38, v37
	s_waitcnt vmcnt(0)
	v_mov_b32_e32 v37, v42
	v_mov_b32_e32 v42, v41
	s_waitcnt lgkmcnt(2)
	v_pk_mul_f32 v[22:23], v[38:39], v[22:23]
	s_waitcnt lgkmcnt(0)
	v_pk_mul_f32 v[24:25], v[42:43], v[24:25]
	v_mov_b32_e32 v44, v36
	v_mov_b32_e32 v36, v40
	v_cndmask_b32_e64 v23, v23, -v23, s[0:1]
	v_cndmask_b32_e64 v22, v22, -v22, s[0:1]
	v_cndmask_b32_e64 v25, v25, -v25, s[0:1]
	v_cndmask_b32_e64 v24, v24, -v24, s[0:1]
	v_pk_fma_f32 v[8:9], v[8:9], v[44:45], v[22:23]
	v_pk_fma_f32 v[10:11], v[10:11], v[36:37], v[24:25]

; __device__ __forceinline__ void phase_fix(KP kp, int l, unsigned char* shm) {
;     ...
;     for (int rb = bid * 32; rb < MT; rb += nb * 32) {
;       const int r = rb + (tid >> 4);
;       const bool samp = r >= MP;
;       const int sr = r - MP;
;       const int pos = samp ? 2048 + (sr & 31) : (r & 4095);
;       const f32x4 x = *(const f32x4*)((const float*)(ws + W_KIRAW) + (size_t)r * 64 + li * 4);
;       float s = x[0] + x[1] + x[2] + x[3];
;       s += __shfl_xor(s, 1); s += __shfl_xor(s, 2); s += __shfl_xor(s, 4); s += __shfl_xor(s, 8);
;       const float mean = s * (1.f / 64.f);
;       const f32x4 d = x - mean;
;       float ss = d[0] * d[0] + d[1] * d[1] + d[2] * d[2] + d[3] * d[3];
;       ss += __shfl_xor(ss, 1); ss += __shfl_xor(ss, 2); ss += __shfl_xor(ss, 4); ss += __shfl_xor(ss, 8);
;       const float rstd = rsqrtf(ss * (1.f / 64.f) + LN_EPS);
;       f32x4 y = d * rstd * gg + bb;
;       f32x4 pr;
; #pragma unroll
;       for (int e = 0; e < 4; ++e) pr[e] = __shfl_xor(y[e], 2);
;       if (li < 4) {
;         const int i0 = (li & 1) * 4;
;         const f32x4 t0 = *(const f32x4*)(rope + (size_t)pos * 16 + i0 * 2), t1 = *(const f32x4*)(rope + (size_t)pos * 16 + i0 * 2 + 4);
;         const float cc[4] = {t0[0], t0[2], t1[0], t1[2]}, sn[4] = {t0[1], t0[3], t1[1], t1[3]};
; #pragma unroll
;         for (int e = 0; e < 4; ++e) y[e] = (li < 2) ? (y[e] * cc[e] - pr[e] * sn[e]) : (pr[e] * sn[e] + y[e] * cc[e]);
;       }
.Lfixki3_t:
	s_or_b64 exec, exec, s[10:11]
	s_waitcnt lgkmcnt(0)
	v_readlane_b32 s4, v255, 2
	v_readlane_b32 s5, v255, 3
	s_add_i32 s23, s23, s4
	v_readlane_b32 s4, v255, 4
	v_readlane_b32 s5, v255, 5
	s_cmp_gt_i32 s23, 0x81ff
	s_nop 0
	v_lshl_add_u64 v[18:19], v[18:19], 0, s[4:5]
	s_cbranch_scc1 .LBB0_2807
	s_mov_b32 s4, 0x800000
	s_mov_b32 s10, 0x8000
	v_mov_b32_e32 v8, v216
	v_mov_b32_e32 v9, v217
	v_mov_b32_e32 v10, v218
	v_mov_b32_e32 v11, v219
	v_add_f32_e32 v16, v8, v9
	v_add_f32_e32 v16, v10, v16
	v_add_f32_e32 v16, v11, v16
	s_nop 1
	v_add_f32_dpp v16, v16, v16 quad_perm:[1,0,3,2] row_mask:0xf bank_mask:0xf
	s_nop 1
	v_add_f32_dpp v16, v16, v16 quad_perm:[2,3,0,1] row_mask:0xf bank_mask:0xf
	s_nop 1
	v_add_f32_dpp v16, v16, v16 row_half_mirror row_mask:0xf bank_mask:0xf
	s_nop 1
	v_add_f32_dpp v16, v16, v16 row_mirror row_mask:0xf bank_mask:0xf
	v_fmamk_f32 v9, v16, 0xbc800000, v9
	v_fmamk_f32 v8, v16, 0xbc800000, v8
	v_fmamk_f32 v11, v16, 0xbc800000, v11
	v_fmac_f32_e32 v10, 0xbc800000, v16
	v_pk_mul_f32 v[24:25], v[8:9], v[8:9]
	v_pk_mul_f32 v[22:23], v[10:11], v[10:11]
	v_add_f32_e32 v16, v24, v25
	v_add_f32_e32 v16, v22, v16
	v_add_f32_e32 v16, v23, v16
	s_nop 1
	v_add_f32_dpp v16, v16, v16 quad_perm:[1,0,3,2] row_mask:0xf bank_mask:0xf
	s_nop 1
	v_add_f32_dpp v16, v16, v16 quad_perm:[2,3,0,1] row_mask:0xf bank_mask:0xf
	s_nop 1
	v_add_f32_dpp v16, v16, v16 row_half_mirror row_mask:0xf bank_mask:0xf
	s_nop 1
	v_add_f32_dpp v16, v16, v16 row_mirror row_mask:0xf bank_mask:0xf
	v_fmamk_f32 v16, v16, 0x3c800000, v249
	v_mul_f32_e32 v21, 0x4b800000, v16
	v_cmp_gt_f32_e32 vcc, s4, v16
	s_movk_i32 s4, 0x7fff
	s_nop 0
	v_cndmask_b32_e32 v16, v16, v21, vcc
	v_rsq_f32_e32 v16, v16
	s_nop 0
	v_mul_f32_e32 v21, 0x45800000, v16
	v_cndmask_b32_e32 v16, v16, v21, vcc
	v_pk_mul_f32 v[8:9], v[8:9], v[16:17] op_sel_hi:[1,0]
	v_pk_mul_f32 v[10:11], v[10:11], v[16:17] op_sel_hi:[1,0]
	v_pk_fma_f32 v[8:9], v[4:5], v[8:9], v[0:1]
	v_pk_fma_f32 v[10:11], v[6:7], v[10:11], v[2:3]
	s_nop 1
	v_mov_b32_dpp v22, v8 quad_perm:[2,3,0,1] row_mask:0xf bank_mask:0xf
	v_mov_b32_dpp v23, v9 quad_perm:[2,3,0,1] row_mask:0xf bank_mask:0xf
	v_mov_b32_dpp v24, v10 quad_perm:[2,3,0,1] row_mask:0xf bank_mask:0xf
	v_mov_b32_dpp v25, v11 quad_perm:[2,3,0,1] row_mask:0xf bank_mask:0xf
	v_add_u32_e32 v21, s23, v28
	v_cmp_lt_i32_e64 s[4:5], s4, v21
	v_cmp_gt_i32_e32 vcc, s10, v21
	s_and_saveexec_b64 s[10:11], s[2:3]
	s_cbranch_execz .Lfixki4_a
	v_and_b32_e32 v16, 0xfff, v21
	v_cndmask_b32_e64 v16, v16, v29, s[4:5]
	v_lshlrev_b32_e32 v16, 6, v16
	v_lshl_add_u64 v[40:41], v[12:13], 0, v[16:17]
	global_load_dwordx4 v[36:39], v[40:41], off
	s_nop 0
	global_load_dwordx4 v[40:43], v[40:41], off offset:16
	s_waitcnt vmcnt(1)
	v_mov_b32_e32 v45, v38
	v_mov_b32_e32 v38, v37
	s_waitcnt vmcnt(0)
	v_mov_b32_e32 v37, v42
	v_mov_b32_e32 v42, v41
	s_waitcnt lgkmcnt(2)
	v_pk_mul_f32 v[22:23], v[38:39], v[22:23]
	s_waitcnt lgkmcnt(0)
	v_pk_mul_f32 v[24:25], v[42:43], v[24:25]
	v_mov_b32_e32 v44, v36
	v_mov_b32_e32 v36, v40
	v_cndmask_b32_e64 v23, v23, -v23, s[0:1]
	v_cndmask_b32_e64 v22, v22, -v22, s[0:1]
	v_cndmask_b32_e64 v25, v25, -v25, s[0:1]
	v_cndmask_b32_e64 v24, v24, -v24, s[0:1]
	v_pk_fma_f32 v[8:9], v[8:9], v[44:45], v[22:23]
	v_pk_fma_f32 v[10:11], v[10:11], v[36:37], v[24:25]
